# sidewait + INB WGM=4 + ATTB table rebuild skip + attention A acc_block barrier without vmcnt drain
# baseline (speedup 1.0000x reference)
; __device__ __forceinline__ void attn_a_phase(Frame& F, const float cshift, const bf16* qkv, const bf16* gate, bf16* y, const float* t5, const float* qg, const float* kg) {
;     ...
;             seg_run<false>(cur, st, L, more ? nxt.kt : nullptr, nxt.vt, zero16, stage, oA0, oA1, lA, oB0, oB1, lB);
;             if (more) seg_start(nxt, st, lane);
;             if ((si == 0 && ui > 0) || si >= 2) __syncthreads();
;             acc_block(cur.first != 0, oA0, oA1, lA, lds, cur.tlocA, lane);
;             if (cur.dual) acc_block(false, oB0, oB1, lB, lds, cur.tlocB, lane);
.LBB0_334:
	s_cmp_eq_u32 s12, 0
	s_cselect_b64 s[30:31], -1, 0
	s_and_b64 s[30:31], s[28:29], s[30:31]
	s_cmp_gt_u32 s12, 1
	s_cselect_b64 s[38:39], -1, 0
	s_or_b64 s[30:31], s[30:31], s[38:39]
	s_andn2_b64 vcc, exec, s[30:31]
	s_cbranch_vccnz .LBB0_336
	s_waitcnt lgkmcnt(0)
	s_barrier

; __global__ void __launch_bounds__(NWAVES * 64, 2) fwd_kernel(Args args) {
;     extern __shared__ __attribute__((aligned(16))) unsigned char lds[];
	.amdhsa_kernel _Z10fwd_kernel4Args
		.amdhsa_group_segment_fixed_size 0
		.amdhsa_private_segment_fixed_size 0
		.amdhsa_kernarg_size 376
		.amdhsa_user_sgpr_count 2
		.amdhsa_user_sgpr_dispatch_ptr 0
		.amdhsa_user_sgpr_queue_ptr 0
		.amdhsa_user_sgpr_kernarg_segment_ptr 1
		.amdhsa_user_sgpr_dispatch_id 0
		.amdhsa_user_sgpr_kernarg_preload_length 0
		.amdhsa_user_sgpr_kernarg_preload_offset 0
		.amdhsa_user_sgpr_private_segment_size 0
		.amdhsa_uses_dynamic_stack 0
		.amdhsa_enable_private_segment 0
		.amdhsa_system_sgpr_workgroup_id_x 1
		.amdhsa_system_sgpr_workgroup_id_y 0
		.amdhsa_system_sgpr_workgroup_id_z 0
		.amdhsa_system_sgpr_workgroup_info 0
		.amdhsa_system_vgpr_workitem_id 0
		.amdhsa_next_free_vgpr 254
		.amdhsa_next_free_sgpr 102
		.amdhsa_accum_offset 256
		.amdhsa_reserve_vcc 1
		.amdhsa_float_round_mode_32 0
		.amdhsa_float_round_mode_16_64 0
		.amdhsa_float_denorm_mode_32 3
		.amdhsa_float_denorm_mode_16_64 3
		.amdhsa_dx10_clamp 1
		.amdhsa_ieee_mode 1
		.amdhsa_fp16_overflow 0
		.amdhsa_tg_split 0
		.amdhsa_exception_fp_ieee_invalid_op 0
		.amdhsa_exception_fp_denorm_src 0
		.amdhsa_exception_fp_ieee_div_zero 0
		.amdhsa_exception_fp_ieee_overflow 0
		.amdhsa_exception_fp_ieee_underflow 0
		.amdhsa_exception_fp_ieee_inexact 0
		.amdhsa_exception_int_div_zero 0
	.end_amdhsa_kernel

; __global__ void __launch_bounds__(NWAVES * 64, 2) fwd_kernel(Args args) {
;     extern __shared__ __attribute__((aligned(16))) unsigned char lds[];
amdhsa.kernels:
  - .agpr_count:     0
    .args:
      - .offset:         0
        .size:           120
        .value_kind:     by_value
      - .offset:         120
        .size:           4
        .value_kind:     hidden_block_count_x
      - .offset:         124
        .size:           4
        .value_kind:     hidden_block_count_y
      - .offset:         128
        .size:           4
        .value_kind:     hidden_block_count_z
      - .offset:         132
        .size:           2
        .value_kind:     hidden_group_size_x
      - .offset:         134
        .size:           2
        .value_kind:     hidden_group_size_y
      - .offset:         136
        .size:           2
        .value_kind:     hidden_group_size_z
      - .offset:         138
        .size:           2
        .value_kind:     hidden_remainder_x
      - .offset:         140
        .size:           2
        .value_kind:     hidden_remainder_y
      - .offset:         142
        .size:           2
        .value_kind:     hidden_remainder_z
      - .offset:         160
        .size:           8
        .value_kind:     hidden_global_offset_x
      - .offset:         168
        .size:           8
        .value_kind:     hidden_global_offset_y
      - .offset:         176
        .size:           8
        .value_kind:     hidden_global_offset_z
      - .offset:         184
        .size:           2
        .value_kind:     hidden_grid_dims
      - .offset:         240
        .size:           4
        .value_kind:     hidden_dynamic_lds_size
    .group_segment_fixed_size: 0
    .kernarg_segment_align: 8
    .kernarg_segment_size: 376
    .language:       OpenCL C
    .language_version:
      - 2
      - 0
    .max_flat_workgroup_size: 512
    .name:           _Z10fwd_kernel4Args
    .private_segment_fixed_size: 0
    .sgpr_count:     108
    .sgpr_spill_count: 113
    .symbol:         _Z10fwd_kernel4Args.kd
    .uniform_work_group_size: 1
    .uses_dynamic_stack: false
    .vgpr_count:     254
    .vgpr_spill_count: 0
    .wavefront_size: 64
